# G1 decay-prefix loop: the two time steps per trip interleaved (independent chains), LDS reads up front
# speedup vs baseline: 1.0021x; 1.0021x over previous
; __device__ __forceinline__ void gla_prep(const Params& p, int tok0, int h, char* lds) {
;     ...
;     float run = 0.f;
;     for (int t = th * 32; t < th * 32 + 32; t++) {
;         float xv = bias;
; #pragma unroll
;         for (int rr = 0; rr < 16; rr++) xv += lrs[t * 16 + rr] * w[rr];
;         const float ls = fminf(xv, 0.f) - __logf(1.f + __expf(-fabsf(xv)));
;         run += ls * (1.f / 16.f);
;         bc[t * 128 + d] = run;
;     }
.LBB0_382:
	v_add_u32_e32 v25, s8, v22
	ds_read_b128 v[26:29], v25
	ds_read_b128 v[30:33], v25 offset:16
	ds_read_b128 v[34:37], v25 offset:32
	ds_read_b128 v[38:41], v25 offset:48
	ds_read_b128 v[42:45], v25 offset:64
	ds_read_b128 v[46:49], v25 offset:80
	ds_read_b128 v[50:53], v25 offset:96
	ds_read_b128 v[54:57], v25 offset:112
	s_addk_i32 s8, 0x80
	s_waitcnt vmcnt(1) lgkmcnt(7)
	s_waitcnt lgkmcnt(3)
	v_fma_f32 v26, v21, v26, v8
	v_fma_f32 v42, v21, v42, v8
	v_fmac_f32_e32 v26, v15, v27
	v_fmac_f32_e32 v42, v15, v43
	v_fmac_f32_e32 v26, v16, v28
	v_fmac_f32_e32 v42, v16, v44
	v_fmac_f32_e32 v26, v17, v29
	v_fmac_f32_e32 v42, v17, v45
	s_waitcnt lgkmcnt(6)
	s_waitcnt lgkmcnt(2)
	v_fmac_f32_e32 v26, v18, v30
	v_fmac_f32_e32 v42, v18, v46
	v_pk_mul_f32 v[32:33], v[0:1], v[32:33]
	v_pk_mul_f32 v[48:49], v[0:1], v[48:49]
	v_fmac_f32_e32 v26, v19, v31
	v_fmac_f32_e32 v42, v19, v47
	v_add_f32_e32 v26, v26, v32
	v_add_f32_e32 v42, v42, v48
	s_waitcnt lgkmcnt(5)
	s_waitcnt lgkmcnt(1)
	v_pk_mul_f32 v[34:35], v[2:3], v[34:35]
	v_pk_mul_f32 v[50:51], v[2:3], v[50:51]
	v_add_f32_e32 v26, v26, v33
	v_add_f32_e32 v42, v42, v49
	v_add_f32_e32 v26, v26, v34
	v_add_f32_e32 v42, v42, v50
	v_pk_mul_f32 v[36:37], v[4:5], v[36:37]
	v_pk_mul_f32 v[52:53], v[4:5], v[52:53]
	v_add_f32_e32 v26, v26, v35
	v_add_f32_e32 v42, v42, v51
	v_add_f32_e32 v26, v26, v36
	v_add_f32_e32 v42, v42, v52
	s_waitcnt lgkmcnt(4)
	s_waitcnt lgkmcnt(0)
	v_pk_mul_f32 v[38:39], v[6:7], v[38:39]
	v_pk_mul_f32 v[54:55], v[6:7], v[54:55]
	v_add_f32_e32 v26, v26, v37
	v_add_f32_e32 v42, v42, v53
	v_add_f32_e32 v26, v26, v38
	v_add_f32_e32 v42, v42, v54
	s_waitcnt vmcnt(0)
	v_pk_mul_f32 v[56:57], v[10:11], v[56:57]
	v_pk_mul_f32 v[40:41], v[10:11], v[40:41]
	v_add_f32_e32 v42, v42, v55
	v_add_f32_e32 v26, v26, v39
	v_add_f32_e32 v42, v42, v56
	v_add_f32_e32 v26, v26, v40
	v_add_f32_e32 v42, v42, v57
	v_add_f32_e32 v26, v26, v41
	v_min_f32_e32 v59, 0, v42
	v_min_f32_e32 v27, 0, v26
	v_mul_f32_e64 v58, |v42|, s41
	v_mul_f32_e64 v26, |v26|, s41
	v_exp_f32_e32 v58, v58
	v_exp_f32_e32 v26, v26
	v_add_f32_e32 v58, 1.0, v58
	v_add_f32_e32 v26, 1.0, v26
	v_cmp_gt_f32_e64 s[48:49], s42, v58
	v_cmp_gt_f32_e32 vcc, s42, v26
	s_nop 1
	s_nop 1
	v_cndmask_b32_e64 v60, 0, 32, s[48:49]
	v_cndmask_b32_e64 v28, 0, 32, vcc
	v_ldexp_f32 v58, v58, v60
	v_ldexp_f32 v26, v26, v28
	v_log_f32_e32 v58, v58
	v_log_f32_e32 v26, v26
	v_cndmask_b32_e64 v60, 0, v20, s[48:49]
	v_cndmask_b32_e32 v28, 0, v20, vcc
	v_mul_f32_e32 v61, 0x3f317217, v58
	v_mul_f32_e32 v29, 0x3f317217, v26
	v_fma_f32 v61, v58, s43, -v61
	v_fma_f32 v29, v26, s43, -v29
	v_fmac_f32_e32 v61, 0x3377d1cf, v58
	v_fmac_f32_e32 v29, 0x3377d1cf, v26
	v_fmac_f32_e32 v61, 0x3f317217, v58
	v_fmac_f32_e32 v29, 0x3f317217, v26
	v_cmp_lt_f32_e64 s[50:51], |v58|, s44
	v_cmp_lt_f32_e64 vcc, |v26|, s44
	s_nop 1
	s_nop 1
	v_cndmask_b32_e64 v58, v58, v61, s[50:51]
	v_cndmask_b32_e32 v26, v26, v29, vcc
	v_sub_f32_e32 v58, v58, v60
	v_sub_f32_e32 v26, v26, v28
	v_sub_f32_e32 v58, v59, v58
	v_sub_f32_e32 v26, v27, v26
	v_fmac_f32_e32 v24, 0x3d800000, v26
	ds_write_b32 v23, v24
	v_fmac_f32_e32 v24, 0x3d800000, v58
	ds_write_b32 v23, v24 offset:512
	v_add_u32_e32 v23, 0x400, v23
	s_cmpk_lg_i32 s8, 0x800
	s_cbranch_scc1 .LBB0_382
	v_cmp_lt_u32_e32 vcc, s40, v13
	s_waitcnt lgkmcnt(0)
	s_barrier
	s_and_saveexec_b64 s[8:9], vcc
	s_cbranch_execz .LBB0_385
	v_lshl_add_u32 v6, v14, 2, s33
	ds_read2st64_b32 v[0:1], v6 offset0:62 offset1:64
	ds_read2st64_b32 v[2:3], v6 offset0:66 offset1:68
	ds_read2st64_b32 v[4:5], v6 offset0:70 offset1:72
	s_waitcnt lgkmcnt(2)
	v_add_f32_e32 v1, v0, v1
	s_waitcnt lgkmcnt(1)
	v_add_f32_e32 v2, v0, v2
	v_add_f32_e32 v7, v0, v3
	ds_write2st64_b32 v6, v1, v2 offset0:64 offset1:66
	ds_read2st64_b32 v[2:3], v6 offset0:74 offset1:76
	s_waitcnt lgkmcnt(2)
	v_add_f32_e32 v1, v0, v4
	ds_write2st64_b32 v6, v7, v1 offset0:68 offset1:70
	v_add_f32_e32 v1, v0, v5
	ds_read2st64_b32 v[4:5], v6 offset0:78 offset1:80
	s_waitcnt lgkmcnt(2)
	v_add_f32_e32 v2, v0, v2
	ds_write2st64_b32 v6, v1, v2 offset0:72 offset1:74
	v_add_f32_e32 v1, v0, v3
	ds_read2st64_b32 v[2:3], v6 offset0:82 offset1:84
	s_waitcnt lgkmcnt(2)
	v_add_f32_e32 v4, v0, v4
	ds_write2st64_b32 v6, v1, v4 offset0:76 offset1:78
	v_add_f32_e32 v1, v0, v5
	ds_read2st64_b32 v[4:5], v6 offset0:86 offset1:88
	s_waitcnt lgkmcnt(2)
	v_add_f32_e32 v2, v0, v2
	ds_write2st64_b32 v6, v1, v2 offset0:80 offset1:82
	v_add_f32_e32 v1, v0, v3
	ds_read2st64_b32 v[2:3], v6 offset0:90 offset1:92
	s_waitcnt lgkmcnt(2)
	v_add_f32_e32 v4, v0, v4
	ds_write2st64_b32 v6, v1, v4 offset0:84 offset1:86
	v_add_f32_e32 v1, v0, v5
	ds_read2st64_b32 v[4:5], v6 offset0:94 offset1:96
	s_waitcnt lgkmcnt(2)
	v_add_f32_e32 v2, v0, v2
	ds_write2st64_b32 v6, v1, v2 offset0:88 offset1:90
	v_add_f32_e32 v1, v0, v3
	ds_read2st64_b32 v[2:3], v6 offset0:98 offset1:100
	s_waitcnt lgkmcnt(2)
	v_add_f32_e32 v4, v0, v4
	ds_write2st64_b32 v6, v1, v4 offset0:92 offset1:94
	v_add_f32_e32 v1, v0, v5
	ds_read2st64_b32 v[4:5], v6 offset0:102 offset1:104
	s_waitcnt lgkmcnt(2)
	v_add_f32_e32 v2, v0, v2
	ds_write2st64_b32 v6, v1, v2 offset0:96 offset1:98
	v_add_f32_e32 v1, v0, v3
	ds_read2st64_b32 v[2:3], v6 offset0:106 offset1:108
	s_waitcnt lgkmcnt(2)
	v_add_f32_e32 v4, v0, v4
	ds_write2st64_b32 v6, v1, v4 offset0:100 offset1:102
	v_add_f32_e32 v1, v0, v5
	ds_read2st64_b32 v[4:5], v6 offset0:110 offset1:112
	s_waitcnt lgkmcnt(2)
	v_add_f32_e32 v2, v0, v2
	ds_write2st64_b32 v6, v1, v2 offset0:104 offset1:106
	v_add_f32_e32 v1, v0, v3
	ds_read2st64_b32 v[2:3], v6 offset0:114 offset1:116
	s_waitcnt lgkmcnt(2)
	v_add_f32_e32 v4, v0, v4
	ds_write2st64_b32 v6, v1, v4 offset0:108 offset1:110
	v_add_f32_e32 v1, v0, v5
	ds_read2st64_b32 v[4:5], v6 offset0:118 offset1:120
	s_waitcnt lgkmcnt(2)
	v_add_f32_e32 v2, v0, v2
	ds_write2st64_b32 v6, v1, v2 offset0:112 offset1:114
	v_add_f32_e32 v1, v0, v3
	ds_read2st64_b32 v[2:3], v6 offset0:122 offset1:124
	s_waitcnt lgkmcnt(2)
	v_add_f32_e32 v4, v0, v4
	ds_write2st64_b32 v6, v1, v4 offset0:116 offset1:118
	ds_read_b32 v1, v6 offset:32256
	v_add_f32_e32 v4, v0, v5
	s_waitcnt lgkmcnt(2)
	v_add_f32_e32 v2, v0, v2
	ds_write2st64_b32 v6, v4, v2 offset0:120 offset1:122
	v_add_f32_e32 v2, v0, v3
	s_waitcnt lgkmcnt(1)
	v_add_f32_e32 v0, v0, v1
	ds_write2st64_b32 v6, v2, v0 offset0:124 offset1:126
